# nt policy on the attention sample units' once-read f32 cache loads; on top of v35
# baseline (speedup 1.0000x reference)
.LBB0_304:
	s_cmp_eq_u32 s46, 32
	s_cselect_b64 s[8:9], -1, 0
	s_cmp_lg_u32 s46, 32
	s_cselect_b64 s[72:73], -1, 0
	s_and_b64 vcc, exec, s[8:9]
	s_cbranch_vccnz .LBB0_311
	s_cmp_gt_u32 s46, 30
	s_mov_b64 s[74:75], -1
	s_cbranch_scc0 .LBB0_309
	v_mov_b32_e32 v8, v2
	v_mov_b32_e32 v9, v2
	v_mov_b32_e32 v3, v2
	v_mov_b32_e32 v4, v2
	v_mov_b32_e32 v5, v2
	v_mov_b32_e32 v6, v2
	v_mov_b32_e32 v7, v2
	s_waitcnt vmcnt(10)
	v_mov_b64_e32 v[112:113], v[8:9]
	s_waitcnt vmcnt(8)
	v_mov_b64_e32 v[120:121], v[8:9]
	v_mov_b64_e32 v[96:97], v[8:9]
	v_mov_b64_e32 v[104:105], v[8:9]
	s_waitcnt vmcnt(2)
	v_mov_b64_e32 v[144:145], v[8:9]
	s_waitcnt vmcnt(0)
	v_mov_b64_e32 v[152:153], v[8:9]
	v_mov_b64_e32 v[128:129], v[8:9]
	v_mov_b64_e32 v[136:137], v[8:9]
	v_mov_b64_e32 v[110:111], v[6:7]
	v_mov_b64_e32 v[108:109], v[4:5]
	v_mov_b64_e32 v[106:107], v[2:3]
	v_mov_b64_e32 v[118:119], v[6:7]
	v_mov_b64_e32 v[116:117], v[4:5]
	v_mov_b64_e32 v[114:115], v[2:3]
	v_mov_b64_e32 v[94:95], v[6:7]
	v_mov_b64_e32 v[92:93], v[4:5]
	v_mov_b64_e32 v[90:91], v[2:3]
	v_mov_b64_e32 v[102:103], v[6:7]
	v_mov_b64_e32 v[100:101], v[4:5]
	v_mov_b64_e32 v[98:99], v[2:3]
	v_mov_b64_e32 v[142:143], v[6:7]
	v_mov_b64_e32 v[140:141], v[4:5]
	v_mov_b64_e32 v[138:139], v[2:3]
	v_mov_b64_e32 v[150:151], v[6:7]
	v_mov_b64_e32 v[148:149], v[4:5]
	v_mov_b64_e32 v[146:147], v[2:3]
	v_mov_b64_e32 v[126:127], v[6:7]
	v_mov_b64_e32 v[124:125], v[4:5]
	v_mov_b64_e32 v[122:123], v[2:3]
	v_mov_b64_e32 v[134:135], v[6:7]
	v_mov_b64_e32 v[132:133], v[4:5]
	v_mov_b64_e32 v[130:131], v[2:3]
	s_and_saveexec_b64 s[74:75], s[4:5]
	s_cbranch_execz .LBB0_308
	global_load_dwordx4 v[94:97], v[190:191], off offset:48 nt
	global_load_dwordx4 v[90:93], v[190:191], off offset:32 nt
	global_load_dwordx4 v[102:105], v[190:191], off offset:16 nt
	global_load_dwordx4 v[98:101], v[190:191], off nt
	global_load_dwordx4 v[110:113], v[190:191], off offset:560 nt
	global_load_dwordx4 v[106:109], v[190:191], off offset:544 nt
	global_load_dwordx4 v[118:121], v[190:191], off offset:528 nt
	global_load_dwordx4 v[114:117], v[190:191], off offset:512 nt
	global_load_dwordx4 v[126:129], v[192:193], off offset:48 nt
	global_load_dwordx4 v[122:125], v[192:193], off offset:32 nt
	global_load_dwordx4 v[134:137], v[192:193], off offset:16 nt
	global_load_dwordx4 v[130:133], v[192:193], off nt
	global_load_dwordx4 v[142:145], v[192:193], off offset:112 nt
	global_load_dwordx4 v[138:141], v[192:193], off offset:96 nt
	global_load_dwordx4 v[150:153], v[192:193], off offset:80 nt
	global_load_dwordx4 v[146:149], v[192:193], off offset:64 nt

.LBB0_309:
	s_andn2_b64 vcc, exec, s[74:75]
	s_cbranch_vccnz .LBB0_311
	v_ashrrev_i32_e32 v195, 31, v194
	v_lshlrev_b64 v[4:5], 13, v[194:195]
	v_lshl_or_b32 v4, s92, 2, v4
	v_lshl_add_u64 v[6:7], v[196:197], 0, v[4:5]
	v_lshl_add_u64 v[4:5], v[188:189], 0, v[4:5]
	global_load_dwordx4 v[94:97], v[6:7], off offset:48 nt
	global_load_dwordx4 v[90:93], v[6:7], off offset:32 nt
	global_load_dwordx4 v[102:105], v[6:7], off offset:16 nt
	global_load_dwordx4 v[98:101], v[6:7], off nt
	global_load_dwordx4 v[110:113], v[6:7], off offset:560 nt
	global_load_dwordx4 v[106:109], v[6:7], off offset:544 nt
	global_load_dwordx4 v[118:121], v[6:7], off offset:528 nt
	global_load_dwordx4 v[114:117], v[6:7], off offset:512 nt
	global_load_dwordx4 v[126:129], v[4:5], off offset:48 nt
	global_load_dwordx4 v[122:125], v[4:5], off offset:32 nt
	global_load_dwordx4 v[134:137], v[4:5], off offset:16 nt
	global_load_dwordx4 v[130:133], v[4:5], off nt
	global_load_dwordx4 v[142:145], v[4:5], off offset:112 nt
	global_load_dwordx4 v[138:141], v[4:5], off offset:96 nt
	global_load_dwordx4 v[150:153], v[4:5], off offset:80 nt
	global_load_dwordx4 v[146:149], v[4:5], off offset:64 nt
